# layer-1 gate/up bias groups computed after the arrival at the split-phase barrier 8 instead of before it (the release now depends on the fix-up rows only)
# speedup vs baseline: 1.0060x; 1.0060x over previous
.Lxb8_rel:
.Lxb8_done:
.LBB0_976:
	s_or_b64 exec, exec, s[4:5]
	s_waitcnt lgkmcnt(0)
	s_barrier
	s_mov_b32 s98, s5
	s_mov_b32 s0, 0
	s_load_dwordx2 s[8:9], s[82:83], 0xb0
	s_cmp_lt_i32 s93, 0
	s_cbranch_scc1 .Lb9_done
	v_mbcnt_lo_u32_b32 v0, -1, s0
	v_mbcnt_hi_u32_b32 v130, -1, v0
	s_lshl_b32 s10, s90, 2
	v_lshlrev_b32_e32 v64, 4, v130
	v_lshlrev_b32_e32 v131, 2, v130
	v_cmp_eq_u32_e64 s[6:7], 0, v130

.Lb9_done:
	s_waitcnt lgkmcnt(0)
	s_mov_b32 s5, s98
	s_load_dwordx2 s[8:9], s[82:83], 0xb0
	s_mov_b32 s36, 0
	s_mov_b32 s0, 0
	s_cmpk_gt_i32 s93, 0x32f
	s_cbranch_scc1 .LBB0_992
	v_mbcnt_lo_u32_b32 v0, -1, s0
	v_mbcnt_hi_u32_b32 v10, -1, v0
	v_lshl_add_u32 v0, v10, 4, s3
	v_add_u32_e32 v1, 0x2000, v0
	v_ashrrev_i32_e32 v2, 31, v1
	v_lshrrev_b32_e32 v2, 22, v2
	v_add_u32_e32 v2, v1, v2
	v_ashrrev_i32_e32 v8, 10, v2
	v_mul_i32_i24_e32 v2, 0x400, v8
	v_sub_u32_e32 v1, v1, v2
	v_lshrrev_b32_e32 v2, 4, v1
	v_bitop3_b32 v1, v2, v1, 32 bitop3:0x6c
	v_ashrrev_i32_e32 v2, 31, v1
	v_lshrrev_b32_e32 v2, 26, v2
	v_add_u32_e32 v2, v1, v2
	v_ashrrev_i32_e32 v9, 6, v2
	v_lshlrev_b32_e32 v3, 3, v8
	v_and_b32_e32 v2, 0xffc0, v2
	v_and_b32_e32 v3, -16, v3
	v_sub_u32_e32 v1, v1, v2
	v_add_u32_e32 v3, v9, v3
	v_lshrrev_b16_e32 v2, 7, v1
	v_and_b32_e32 v4, 3, v9
	s_mov_b32 s0, 0x1fffe0
	v_lshrrev_b32_e32 v5, 2, v3
	v_lshlrev_b32_e32 v6, 1, v3
	v_and_b32_e32 v2, 1, v2
	v_and_or_b32 v4, v3, s0, v4
	v_and_b32_e32 v5, 4, v5
	v_and_b32_e32 v6, 24, v6
	v_add_u16_e32 v1, v1, v2
	v_mov_b32_e32 v2, 1
	v_or3_b32 v4, v4, v5, v6
	v_lshlrev_b32_e32 v5, 5, v8
	v_ashrrev_i16_sdwa v1, v2, sext(v1) dst_sel:DWORD dst_unused:UNUSED_PAD src0_sel:DWORD src1_sel:BYTE_0
	v_and_b32_e32 v5, 32, v5
	v_bfe_i32 v11, v1, 0, 16
	v_add_lshl_u32 v1, v5, v11, 1
	v_lshl_add_u32 v144, v4, 11, v1
	v_lshl_add_u32 v146, v3, 11, v1
	v_ashrrev_i32_e32 v1, 31, v0
	v_lshrrev_b32_e32 v1, 22, v1
	v_add_u32_e32 v1, v0, v1
	v_ashrrev_i32_e32 v12, 10, v1
	v_mul_i32_i24_e32 v1, 0x400, v12
	v_sub_u32_e32 v0, v0, v1
	v_lshrrev_b32_e32 v1, 4, v0
	v_bitop3_b32 v0, v1, v0, 32 bitop3:0x6c
	v_ashrrev_i32_e32 v1, 31, v0
	v_lshrrev_b32_e32 v1, 26, v1
	s_waitcnt lgkmcnt(0)
	s_add_u32 s37, s8, 0x7400000
	v_add_u32_e32 v1, v0, v1
	v_lshlrev_b32_e32 v3, 3, v12
	s_addc_u32 s38, s9, 0
	v_ashrrev_i32_e32 v13, 6, v1
	v_and_b32_e32 v3, -16, v3
	s_add_u32 s39, s8, 0x1700000
	v_add_u32_e32 v3, v13, v3
	v_and_b32_e32 v4, 3, v13
	s_addc_u32 s40, s9, 0
	v_and_or_b32 v4, v3, s0, v4
	s_ashr_i32 s0, s93, 31
	s_lshr_b32 s0, s0, 29
	s_add_i32 s0, s93, s0
	s_ashr_i32 s1, s0, 3
	s_and_b32 s0, s0, -8
	s_sub_i32 s0, s93, s0
	s_cmp_lt_i32 s0, 0
	s_movk_i32 s41, 0x67
	s_cselect_b32 s2, s41, 0x66
	s_mul_i32 s0, s0, s2
	s_add_i32 s0, s0, s1
	s_mul_hi_i32 s1, s0, 0x2aaaaaab
	s_lshr_b32 s2, s1, 31
	s_ashr_i32 s1, s1, 3
	s_add_i32 s1, s1, s2
	s_lshl_b32 s2, s1, 2
	s_mul_i32 s1, s1, 48
	s_sub_i32 s0, s0, s1
	s_bfe_i32 s1, s0, 0x80000
	s_bfe_u32 s1, s1, 0x2000d
	s_add_i32 s1, s0, s1
	s_bfe_i32 s4, s1, 0x80000
	s_and_b32 s1, s1, 0xfc
	s_sub_i32 s0, s0, s1
	s_sext_i32_i16 s4, s4
	s_sext_i32_i8 s0, s0
	v_lshrrev_b32_e32 v5, 2, v3
	v_lshlrev_b32_e32 v6, 1, v3
	v_and_b32_e32 v1, 0xc0, v1
	s_lshr_b32 s4, s4, 2
	s_add_i32 s26, s2, s0
	v_and_b32_e32 v5, 4, v5
	v_and_b32_e32 v6, 24, v6
	v_sub_u32_e32 v0, v0, v1
	s_ashr_i32 s27, s26, 31
	s_bfe_i64 s[6:7], s[4:5], 0x100000
	v_or3_b32 v4, v4, v5, v6
	v_lshlrev_b32_e32 v5, 5, v12
	v_ashrrev_i16_sdwa v0, v2, sext(v0) dst_sel:DWORD dst_unused:UNUSED_PAD src0_sel:DWORD src1_sel:BYTE_0
	s_lshl_b64 s[0:1], s[26:27], 19
	s_lshl_b64 s[6:7], s[6:7], 19
	v_and_b32_e32 v5, 32, v5
	v_bfe_i32 v14, v0, 0, 16
	s_add_u32 s30, s39, s6
	v_add_lshl_u32 v0, v5, v14, 1
	s_addc_u32 s31, s40, s7
	s_add_i32 s27, s3, 0
	v_lshl_add_u32 v148, v4, 11, v0
	s_add_i32 m0, s27, 0x10000
	v_lshl_add_u32 v150, v3, 11, v0
	global_load_lds_dwordx4 v148, s[30:31]
	s_add_i32 m0, s27, 0x12000
	s_add_u32 s6, s30, 0x40000
	global_load_lds_dwordx4 v144, s[30:31]
	s_addc_u32 s7, s31, 0
	s_add_i32 m0, s27, 0x14000
	v_mov_b32_e32 v149, 0
	global_load_lds_dwordx4 v148, s[6:7]
	s_add_i32 m0, s27, 0x16000
	s_add_u32 s28, s37, s0
	s_addc_u32 s29, s38, s1
	s_add_i32 s42, s27, 0x2000
	global_load_lds_dwordx4 v144, s[6:7]
	s_mov_b32 m0, s27
	s_add_u32 s0, s28, 0x40000
	global_load_lds_dwordx4 v150, s[28:29]
	s_mov_b32 m0, s42
	s_addc_u32 s1, s29, 0
	s_add_i32 s43, s27, 0x4000
	global_load_lds_dwordx4 v146, s[28:29]
	s_mov_b32 m0, s43
	s_add_i32 s44, s27, 0x6000
	global_load_lds_dwordx4 v150, s[0:1]
	s_mov_b32 m0, s44
	v_mov_b32_e32 v145, v149
	global_load_lds_dwordx4 v146, s[0:1]
	v_mov_b32_e32 v151, v149
	v_mov_b32_e32 v147, v149
	s_cmp_eq_u32 s84, 1
	s_mov_b32 s45, 0
	v_lshl_add_u64 v[6:7], s[30:31], 0, v[148:149]
	v_lshl_add_u64 v[4:5], s[30:31], 0, v[144:145]
	v_lshl_add_u64 v[0:1], s[28:29], 0, v[150:151]
	s_cselect_b64 s[10:11], -1, 0
	s_cmp_lg_u32 s84, 1
	v_lshl_add_u64 v[2:3], s[28:29], 0, v[146:147]
	s_cbranch_scc1 .LBB0_979
	s_barrier
